# ctx-pool tokens spread over all 256 WGs; w_in epilogue bias loads hoisted before stores (no mid-epilogue vmcnt drain)
# speedup vs baseline: 1.0094x; 1.0094x over previous
.LBB0_482:
	v_lshl_add_u32 v152, s34, 8, v162
	v_ashrrev_i32_e32 v153, 31, v152
	v_lshl_add_u64 v[158:159], v[152:153], 2, s[46:47]
	global_load_dword v156, v[158:159], off
	s_lshl_b64 s[0:1], s[22:23], 2
	v_lshl_or_b32 v150, s31, 8, v164
	s_add_u32 s0, s18, s0
	s_addc_u32 s1, s19, s1
	v_ashrrev_i32_e32 v151, 31, v150
	v_lshl_add_u64 v[154:155], v[150:151], 2, s[0:1]
	global_load_dwordx4 v[100:103], v[154:155], off offset:16
	global_load_dwordx4 v[104:107], v[154:155], off
	global_load_dwordx4 v[200:203], v[154:155], off offset:512
	global_load_dwordx4 v[204:207], v[154:155], off offset:528
	global_load_dword v176, v[158:159], off offset:64
	global_load_dword v175, v[158:159], off offset:128
	global_load_dword v174, v[158:159], off offset:192
	global_load_dword v173, v[158:159], off offset:512
	global_load_dword v172, v[158:159], off offset:576
	global_load_dword v157, v[158:159], off offset:640
	global_load_dword v153, v[158:159], off offset:704
	s_cmp_lt_i32 s31, 2
	s_cselect_b64 s[22:23], -1, 0
	s_cmp_gt_i32 s31, 1
	s_waitcnt vmcnt(0)
	v_fmamk_f32 v156, v156, 0x3a800000, v1
	v_mul_f32_e32 v158, 0x4b800000, v156
	v_cmp_gt_f32_e32 vcc, s74, v156
	s_nop 1
	v_cndmask_b32_e32 v156, v156, v158, vcc
	v_rsq_f32_e32 v156, v156
	s_nop 0
	v_mul_f32_e32 v158, 0x45800000, v156
	v_cndmask_b32_e32 v156, v156, v158, vcc
	v_pk_fma_f32 v[138:139], v[138:139], v[156:157], v[106:107] op_sel_hi:[1,0,1]
	v_pk_fma_f32 v[136:137], v[136:137], v[156:157], v[104:105] op_sel_hi:[1,0,1]
	v_pk_fma_f32 v[158:159], v[134:135], v[156:157], v[102:103] op_sel_hi:[1,0,1]
	v_pk_fma_f32 v[160:161], v[132:133], v[156:157], v[100:101] op_sel_hi:[1,0,1]
	s_cbranch_scc1 .LBB0_484
	v_mul_f32_e32 v133, 0xbfb8aa3b, v160
	v_exp_f32_e32 v133, v133
	v_mul_f32_e32 v132, 0xbfb8aa3b, v136
	v_exp_f32_e32 v132, v132
	v_mul_f32_e32 v167, 0xbfb8aa3b, v158
	v_add_f32_e32 v133, 1.0, v133
	v_rcp_f32_e32 v134, v133
	v_mul_f32_e32 v133, 0xbfb8aa3b, v137
	v_exp_f32_e32 v133, v133
	v_add_f32_e32 v132, 1.0, v132
	v_exp_f32_e32 v167, v167
	v_rcp_f32_e32 v132, v132
	v_add_f32_e32 v133, 1.0, v133
	v_rcp_f32_e32 v133, v133
	v_add_f32_e32 v167, 1.0, v167
	v_mul_f32_e32 v135, 0xbfb8aa3b, v161
	v_mul_f32_e32 v166, 0xbfb8aa3b, v138
	v_rcp_f32_e32 v168, v167
	v_mul_f32_e32 v167, 0xbfb8aa3b, v139
	v_pk_mul_f32 v[136:137], v[136:137], v[132:133]
	v_mul_f32_e32 v132, 0xbfb8aa3b, v159
	v_exp_f32_e32 v135, v135
	v_exp_f32_e32 v166, v166
	v_exp_f32_e32 v167, v167
	v_exp_f32_e32 v132, v132
	v_add_f32_e32 v135, 1.0, v135
	v_add_f32_e32 v166, 1.0, v166
	v_add_f32_e32 v167, 1.0, v167
	v_add_f32_e32 v132, 1.0, v132
	v_rcp_f32_e32 v135, v135
	v_rcp_f32_e32 v166, v166
	v_rcp_f32_e32 v167, v167
	v_rcp_f32_e32 v169, v132
	v_pk_mul_f32 v[160:161], v[160:161], v[134:135]
	v_pk_mul_f32 v[138:139], v[138:139], v[166:167]
	v_pk_mul_f32 v[158:159], v[158:159], v[168:169]

.LBB0_498:
	v_add_u32_e32 v79, 0xb0, v152
	v_mov_b64_e32 v[80:81], s[44:45]
	v_mad_i64_i32 v[80:81], s[0:1], v79, s78, v[80:81]
	v_lshl_add_u64 v[80:81], v[150:151], 1, v[80:81]
	v_cvt_pk_bf16_f32 v72, v72, v73
	v_cvt_pk_bf16_f32 v73, v74, v75
	v_cvt_pk_bf16_f32 v74, v68, v69
	v_cvt_pk_bf16_f32 v75, v70, v71
	global_store_dwordx4 v[80:81], v[72:75], off
	v_mov_b32_e32 v157, v156
	v_mov_b32_e32 v82, v156
	v_mov_b32_e32 v83, v156
	s_and_b64 vcc, exec, s[40:41]
	v_pk_fma_f32 v[66:67], v[66:67], v[82:83], v[202:203]
	v_pk_fma_f32 v[64:65], v[64:65], v[156:157], v[200:201]
	v_pk_fma_f32 v[62:63], v[62:63], v[82:83], v[206:207]
	v_pk_fma_f32 v[60:61], v[60:61], v[156:157], v[204:205]
	s_cbranch_vccnz .LBB0_500
	v_mul_f32_e32 v79, 0xbfb8aa3b, v64
	v_exp_f32_e32 v79, v79
	s_nop 0
	v_add_f32_e32 v79, 1.0, v79
	v_rcp_f32_e32 v82, v79
	v_mul_f32_e32 v79, 0xbfb8aa3b, v60
	v_exp_f32_e32 v79, v79
	s_nop 0
	v_add_f32_e32 v79, 1.0, v79
	v_rcp_f32_e32 v88, v79
	v_mul_f32_e32 v79, 0xbfb8aa3b, v65
	v_exp_f32_e32 v79, v79
	s_nop 0
	v_add_f32_e32 v79, 1.0, v79
	v_rcp_f32_e32 v83, v79
	v_mul_f32_e32 v79, 0xbfb8aa3b, v61
	v_exp_f32_e32 v79, v79
	v_pk_mul_f32 v[64:65], v[64:65], v[82:83]
	v_add_f32_e32 v79, 1.0, v79
	v_rcp_f32_e32 v89, v79
	v_mul_f32_e32 v79, 0xbfb8aa3b, v66
	v_exp_f32_e32 v79, v79
	v_pk_mul_f32 v[60:61], v[60:61], v[88:89]
	v_add_f32_e32 v79, 1.0, v79
	v_rcp_f32_e32 v90, v79
	v_mul_f32_e32 v79, 0xbfb8aa3b, v62
	v_exp_f32_e32 v79, v79
	s_nop 0
	v_add_f32_e32 v79, 1.0, v79
	v_rcp_f32_e32 v96, v79
	v_mul_f32_e32 v79, 0xbfb8aa3b, v67
	v_exp_f32_e32 v79, v79
	s_nop 0
	v_add_f32_e32 v79, 1.0, v79
	v_rcp_f32_e32 v91, v79
	v_mul_f32_e32 v79, 0xbfb8aa3b, v63
	v_exp_f32_e32 v79, v79
	v_pk_mul_f32 v[66:67], v[66:67], v[90:91]
	v_add_f32_e32 v79, 1.0, v79
	v_rcp_f32_e32 v97, v79
	s_nop 0
	v_pk_mul_f32 v[62:63], v[62:63], v[96:97]
.LBB0_500:
	v_mov_b32_e32 v133, v132
	v_cvt_pk_bf16_f32 v64, v64, v65
	v_cvt_pk_bf16_f32 v65, v66, v67
	v_cvt_pk_bf16_f32 v66, v60, v61
	v_mov_b32_e32 v60, v132
	v_mov_b32_e32 v61, v132
	v_cvt_pk_bf16_f32 v67, v62, v63
	v_pk_fma_f32 v[58:59], v[58:59], v[60:61], v[202:203]
	v_pk_fma_f32 v[56:57], v[56:57], v[132:133], v[200:201]
	v_pk_fma_f32 v[54:55], v[54:55], v[60:61], v[206:207]
	s_and_b64 vcc, exec, s[40:41]
	v_pk_fma_f32 v[52:53], v[52:53], v[132:133], v[204:205]
	global_store_dwordx4 v[134:135], v[64:67], off offset:256
	s_cbranch_vccnz .LBB0_502
	v_mul_f32_e32 v61, 0xbfb8aa3b, v52
	v_exp_f32_e32 v61, v61
	v_mul_f32_e32 v60, 0xbfb8aa3b, v56
	v_exp_f32_e32 v60, v60
	v_mul_f32_e32 v65, 0xbfb8aa3b, v54
	v_add_f32_e32 v61, 1.0, v61
	v_rcp_f32_e32 v62, v61
	v_mul_f32_e32 v61, 0xbfb8aa3b, v57
	v_exp_f32_e32 v61, v61
	v_add_f32_e32 v60, 1.0, v60
	v_exp_f32_e32 v65, v65
	v_rcp_f32_e32 v60, v60
	v_add_f32_e32 v61, 1.0, v61
	v_rcp_f32_e32 v61, v61
	v_add_f32_e32 v65, 1.0, v65
	v_mul_f32_e32 v63, 0xbfb8aa3b, v53
	v_mul_f32_e32 v64, 0xbfb8aa3b, v58
	v_rcp_f32_e32 v66, v65
	v_mul_f32_e32 v65, 0xbfb8aa3b, v59
	v_pk_mul_f32 v[56:57], v[56:57], v[60:61]
	v_mul_f32_e32 v60, 0xbfb8aa3b, v55
	v_exp_f32_e32 v63, v63
	v_exp_f32_e32 v64, v64
	v_exp_f32_e32 v65, v65
	v_exp_f32_e32 v60, v60
	v_add_f32_e32 v63, 1.0, v63
	v_add_f32_e32 v64, 1.0, v64
	v_add_f32_e32 v65, 1.0, v65
	v_add_f32_e32 v60, 1.0, v60
	v_rcp_f32_e32 v63, v63
	v_rcp_f32_e32 v64, v64
	v_rcp_f32_e32 v65, v65
	v_rcp_f32_e32 v67, v60
	v_pk_mul_f32 v[52:53], v[52:53], v[62:63]
	v_pk_mul_f32 v[58:59], v[58:59], v[64:65]
	v_pk_mul_f32 v[54:55], v[54:55], v[66:67]
.LBB0_502:
	v_mov_b32_e32 v127, v126
	v_cvt_pk_bf16_f32 v56, v56, v57
	v_cvt_pk_bf16_f32 v57, v58, v59
	v_cvt_pk_bf16_f32 v58, v52, v53
	v_mov_b32_e32 v52, v126
	v_mov_b32_e32 v53, v126
	v_cvt_pk_bf16_f32 v59, v54, v55
	v_pk_fma_f32 v[50:51], v[50:51], v[52:53], v[202:203]
	v_pk_fma_f32 v[48:49], v[48:49], v[126:127], v[200:201]
	v_pk_fma_f32 v[46:47], v[46:47], v[52:53], v[206:207]
	s_and_b64 vcc, exec, s[40:41]
	v_pk_fma_f32 v[44:45], v[44:45], v[126:127], v[204:205]
	global_store_dwordx4 v[124:125], v[56:59], off offset:256
	s_cbranch_vccnz .LBB0_504
	v_mul_f32_e32 v53, 0xbfb8aa3b, v44
	v_exp_f32_e32 v53, v53
	v_mul_f32_e32 v52, 0xbfb8aa3b, v48
	v_exp_f32_e32 v52, v52
	v_mul_f32_e32 v57, 0xbfb8aa3b, v46
	v_add_f32_e32 v53, 1.0, v53
	v_rcp_f32_e32 v54, v53
	v_mul_f32_e32 v53, 0xbfb8aa3b, v49
	v_exp_f32_e32 v53, v53
	v_add_f32_e32 v52, 1.0, v52
	v_exp_f32_e32 v57, v57
	v_rcp_f32_e32 v52, v52
	v_add_f32_e32 v53, 1.0, v53
	v_rcp_f32_e32 v53, v53
	v_add_f32_e32 v57, 1.0, v57
	v_mul_f32_e32 v55, 0xbfb8aa3b, v45
	v_mul_f32_e32 v56, 0xbfb8aa3b, v50
	v_rcp_f32_e32 v58, v57
	v_mul_f32_e32 v57, 0xbfb8aa3b, v51
	v_pk_mul_f32 v[48:49], v[48:49], v[52:53]
	v_mul_f32_e32 v52, 0xbfb8aa3b, v47
	v_exp_f32_e32 v55, v55
	v_exp_f32_e32 v56, v56
	v_exp_f32_e32 v57, v57
	v_exp_f32_e32 v52, v52
	v_add_f32_e32 v55, 1.0, v55
	v_add_f32_e32 v56, 1.0, v56
	v_add_f32_e32 v57, 1.0, v57
	v_add_f32_e32 v52, 1.0, v52
	v_rcp_f32_e32 v55, v55
	v_rcp_f32_e32 v56, v56
	v_rcp_f32_e32 v57, v57
	v_rcp_f32_e32 v59, v52
	v_pk_mul_f32 v[44:45], v[44:45], v[54:55]
	v_pk_mul_f32 v[50:51], v[50:51], v[56:57]
	v_pk_mul_f32 v[46:47], v[46:47], v[58:59]
.LBB0_504:
	v_mov_b32_e32 v119, v118
	v_cvt_pk_bf16_f32 v48, v48, v49
	v_cvt_pk_bf16_f32 v49, v50, v51
	v_cvt_pk_bf16_f32 v50, v44, v45
	v_mov_b32_e32 v44, v118
	v_mov_b32_e32 v45, v118
	v_cvt_pk_bf16_f32 v51, v46, v47
	v_pk_fma_f32 v[42:43], v[42:43], v[44:45], v[202:203]
	v_pk_fma_f32 v[40:41], v[40:41], v[118:119], v[200:201]
	v_pk_fma_f32 v[38:39], v[38:39], v[44:45], v[206:207]
	s_and_b64 vcc, exec, s[40:41]
	v_pk_fma_f32 v[36:37], v[36:37], v[118:119], v[204:205]
	global_store_dwordx4 v[116:117], v[48:51], off offset:256
	s_cbranch_vccnz .LBB0_506
	v_mul_f32_e32 v45, 0xbfb8aa3b, v36
	v_exp_f32_e32 v45, v45
	v_mul_f32_e32 v44, 0xbfb8aa3b, v40
	v_exp_f32_e32 v44, v44
	v_mul_f32_e32 v49, 0xbfb8aa3b, v38
	v_add_f32_e32 v45, 1.0, v45
	v_rcp_f32_e32 v46, v45
	v_mul_f32_e32 v45, 0xbfb8aa3b, v41
	v_exp_f32_e32 v45, v45
	v_add_f32_e32 v44, 1.0, v44
	v_exp_f32_e32 v49, v49
	v_rcp_f32_e32 v44, v44
	v_add_f32_e32 v45, 1.0, v45
	v_rcp_f32_e32 v45, v45
	v_add_f32_e32 v49, 1.0, v49
	v_mul_f32_e32 v47, 0xbfb8aa3b, v37
	v_mul_f32_e32 v48, 0xbfb8aa3b, v42
	v_rcp_f32_e32 v50, v49
	v_mul_f32_e32 v49, 0xbfb8aa3b, v43
	v_pk_mul_f32 v[40:41], v[40:41], v[44:45]
	v_mul_f32_e32 v44, 0xbfb8aa3b, v39
	v_exp_f32_e32 v47, v47
	v_exp_f32_e32 v48, v48
	v_exp_f32_e32 v49, v49
	v_exp_f32_e32 v44, v44
	v_add_f32_e32 v47, 1.0, v47
	v_add_f32_e32 v48, 1.0, v48
	v_add_f32_e32 v49, 1.0, v49
	v_add_f32_e32 v44, 1.0, v44
	v_rcp_f32_e32 v47, v47
	v_rcp_f32_e32 v48, v48
	v_rcp_f32_e32 v49, v49
	v_rcp_f32_e32 v51, v44
	v_pk_mul_f32 v[36:37], v[36:37], v[46:47]
	v_pk_mul_f32 v[42:43], v[42:43], v[48:49]
	v_pk_mul_f32 v[38:39], v[38:39], v[50:51]
.LBB0_506:
	v_mov_b32_e32 v111, v110
	v_cvt_pk_bf16_f32 v40, v40, v41
	v_cvt_pk_bf16_f32 v41, v42, v43
	v_cvt_pk_bf16_f32 v42, v36, v37
	v_mov_b32_e32 v36, v110
	v_mov_b32_e32 v37, v110
	v_cvt_pk_bf16_f32 v43, v38, v39
	v_pk_fma_f32 v[34:35], v[34:35], v[36:37], v[202:203]
	v_pk_fma_f32 v[32:33], v[32:33], v[110:111], v[200:201]
	v_pk_fma_f32 v[30:31], v[30:31], v[36:37], v[206:207]
	s_and_b64 vcc, exec, s[40:41]
	v_pk_fma_f32 v[28:29], v[28:29], v[110:111], v[204:205]
	global_store_dwordx4 v[108:109], v[40:43], off offset:256
	s_cbranch_vccnz .LBB0_508
	v_mul_f32_e32 v37, 0xbfb8aa3b, v28
	v_exp_f32_e32 v37, v37
	v_mul_f32_e32 v36, 0xbfb8aa3b, v32
	v_exp_f32_e32 v36, v36
	v_mul_f32_e32 v41, 0xbfb8aa3b, v30
	v_add_f32_e32 v37, 1.0, v37
	v_rcp_f32_e32 v38, v37
	v_mul_f32_e32 v37, 0xbfb8aa3b, v33
	v_exp_f32_e32 v37, v37
	v_add_f32_e32 v36, 1.0, v36
	v_exp_f32_e32 v41, v41
	v_rcp_f32_e32 v36, v36
	v_add_f32_e32 v37, 1.0, v37
	v_rcp_f32_e32 v37, v37
	v_add_f32_e32 v41, 1.0, v41
	v_mul_f32_e32 v39, 0xbfb8aa3b, v29
	v_mul_f32_e32 v40, 0xbfb8aa3b, v34
	v_rcp_f32_e32 v42, v41
	v_mul_f32_e32 v41, 0xbfb8aa3b, v35
	v_pk_mul_f32 v[32:33], v[32:33], v[36:37]
	v_mul_f32_e32 v36, 0xbfb8aa3b, v31
	v_exp_f32_e32 v39, v39
	v_exp_f32_e32 v40, v40
	v_exp_f32_e32 v41, v41
	v_exp_f32_e32 v36, v36
	v_add_f32_e32 v39, 1.0, v39
	v_add_f32_e32 v40, 1.0, v40
	v_add_f32_e32 v41, 1.0, v41
	v_add_f32_e32 v36, 1.0, v36
	v_rcp_f32_e32 v39, v39
	v_rcp_f32_e32 v40, v40
	v_rcp_f32_e32 v41, v41
	v_rcp_f32_e32 v43, v36
	v_pk_mul_f32 v[28:29], v[28:29], v[38:39]
	v_pk_mul_f32 v[34:35], v[34:35], v[40:41]
	v_pk_mul_f32 v[30:31], v[30:31], v[42:43]
.LBB0_508:
	v_mov_b32_e32 v95, v94
	v_cvt_pk_bf16_f32 v32, v32, v33
	v_cvt_pk_bf16_f32 v33, v34, v35
	v_cvt_pk_bf16_f32 v34, v28, v29
	v_mov_b32_e32 v28, v94
	v_mov_b32_e32 v29, v94
	v_cvt_pk_bf16_f32 v35, v30, v31
	v_pk_fma_f32 v[24:25], v[24:25], v[28:29], v[202:203]
	v_pk_fma_f32 v[22:23], v[22:23], v[94:95], v[200:201]
	v_pk_fma_f32 v[20:21], v[20:21], v[28:29], v[206:207]
	s_and_b64 vcc, exec, s[40:41]
	v_pk_fma_f32 v[18:19], v[18:19], v[94:95], v[204:205]
	global_store_dwordx4 v[92:93], v[32:35], off offset:256
	s_cbranch_vccnz .LBB0_510
	v_mul_f32_e32 v29, 0xbfb8aa3b, v18
	v_exp_f32_e32 v29, v29
	v_mul_f32_e32 v28, 0xbfb8aa3b, v22
	v_exp_f32_e32 v28, v28
	v_mul_f32_e32 v33, 0xbfb8aa3b, v20
	v_add_f32_e32 v29, 1.0, v29
	v_rcp_f32_e32 v30, v29
	v_mul_f32_e32 v29, 0xbfb8aa3b, v23
	v_exp_f32_e32 v29, v29
	v_add_f32_e32 v28, 1.0, v28
	v_exp_f32_e32 v33, v33
	v_rcp_f32_e32 v28, v28
	v_add_f32_e32 v29, 1.0, v29
	v_rcp_f32_e32 v29, v29
	v_add_f32_e32 v33, 1.0, v33
	v_mul_f32_e32 v31, 0xbfb8aa3b, v19
	v_mul_f32_e32 v32, 0xbfb8aa3b, v24
	v_rcp_f32_e32 v34, v33
	v_mul_f32_e32 v33, 0xbfb8aa3b, v25
	v_pk_mul_f32 v[22:23], v[22:23], v[28:29]
	v_mul_f32_e32 v28, 0xbfb8aa3b, v21
	v_exp_f32_e32 v31, v31
	v_exp_f32_e32 v32, v32
	v_exp_f32_e32 v33, v33
	v_exp_f32_e32 v28, v28
	v_add_f32_e32 v31, 1.0, v31
	v_add_f32_e32 v32, 1.0, v32
	v_add_f32_e32 v33, 1.0, v33
	v_add_f32_e32 v28, 1.0, v28
	v_rcp_f32_e32 v31, v31
	v_rcp_f32_e32 v32, v32
	v_rcp_f32_e32 v33, v33
	v_rcp_f32_e32 v35, v28
	v_pk_mul_f32 v[18:19], v[18:19], v[30:31]
	v_pk_mul_f32 v[24:25], v[24:25], v[32:33]
	v_pk_mul_f32 v[20:21], v[20:21], v[34:35]
.LBB0_510:
	v_mov_b32_e32 v87, v86
	v_cvt_pk_bf16_f32 v22, v22, v23
	v_cvt_pk_bf16_f32 v23, v24, v25
	v_cvt_pk_bf16_f32 v24, v18, v19
	v_mov_b32_e32 v18, v86
	v_mov_b32_e32 v19, v86
	v_cvt_pk_bf16_f32 v25, v20, v21
	v_pk_fma_f32 v[16:17], v[16:17], v[18:19], v[202:203]
	v_pk_fma_f32 v[14:15], v[14:15], v[86:87], v[200:201]
	v_pk_fma_f32 v[12:13], v[12:13], v[18:19], v[206:207]
	s_and_b64 vcc, exec, s[40:41]
	v_pk_fma_f32 v[10:11], v[10:11], v[86:87], v[204:205]
	global_store_dwordx4 v[84:85], v[22:25], off offset:256
	s_cbranch_vccnz .LBB0_512
	v_mul_f32_e32 v19, 0xbfb8aa3b, v10
	v_exp_f32_e32 v19, v19
	v_mul_f32_e32 v18, 0xbfb8aa3b, v14
	v_exp_f32_e32 v18, v18
	v_mul_f32_e32 v23, 0xbfb8aa3b, v12
	v_add_f32_e32 v19, 1.0, v19
	v_rcp_f32_e32 v20, v19
	v_mul_f32_e32 v19, 0xbfb8aa3b, v15
	v_exp_f32_e32 v19, v19
	v_add_f32_e32 v18, 1.0, v18
	v_exp_f32_e32 v23, v23
	v_rcp_f32_e32 v18, v18
	v_add_f32_e32 v19, 1.0, v19
	v_rcp_f32_e32 v19, v19
	v_add_f32_e32 v23, 1.0, v23
	v_mul_f32_e32 v21, 0xbfb8aa3b, v11
	v_mul_f32_e32 v22, 0xbfb8aa3b, v16
	v_rcp_f32_e32 v24, v23
	v_mul_f32_e32 v23, 0xbfb8aa3b, v17
	v_pk_mul_f32 v[14:15], v[14:15], v[18:19]
	v_mul_f32_e32 v18, 0xbfb8aa3b, v13
	v_exp_f32_e32 v21, v21
	v_exp_f32_e32 v22, v22
	v_exp_f32_e32 v23, v23
	v_exp_f32_e32 v18, v18
	v_add_f32_e32 v21, 1.0, v21
	v_add_f32_e32 v22, 1.0, v22
	v_add_f32_e32 v23, 1.0, v23
	v_add_f32_e32 v18, 1.0, v18
	v_rcp_f32_e32 v21, v21
	v_rcp_f32_e32 v22, v22
	v_rcp_f32_e32 v23, v23
	v_rcp_f32_e32 v25, v18
	v_pk_mul_f32 v[10:11], v[10:11], v[20:21]
	v_pk_mul_f32 v[16:17], v[16:17], v[22:23]
	v_pk_mul_f32 v[12:13], v[12:13], v[24:25]
.LBB0_512:
	v_mov_b32_e32 v79, v78
	v_cvt_pk_bf16_f32 v14, v14, v15
	v_cvt_pk_bf16_f32 v15, v16, v17
	v_cvt_pk_bf16_f32 v16, v10, v11
	v_mov_b32_e32 v10, v78
	v_mov_b32_e32 v11, v78
	v_cvt_pk_bf16_f32 v17, v12, v13
	v_pk_fma_f32 v[8:9], v[8:9], v[10:11], v[202:203]
	v_pk_fma_f32 v[6:7], v[6:7], v[78:79], v[200:201]
	v_pk_fma_f32 v[4:5], v[4:5], v[10:11], v[206:207]
	s_and_b64 vcc, exec, s[40:41]
	v_pk_fma_f32 v[2:3], v[2:3], v[78:79], v[204:205]
	global_store_dwordx4 v[76:77], v[14:17], off offset:256
	s_cbranch_vccnz .LBB0_475
	v_mul_f32_e32 v11, 0xbfb8aa3b, v2
	v_exp_f32_e32 v11, v11
	v_mul_f32_e32 v10, 0xbfb8aa3b, v6
	v_exp_f32_e32 v10, v10
	v_mul_f32_e32 v15, 0xbfb8aa3b, v4
	v_add_f32_e32 v11, 1.0, v11
	v_rcp_f32_e32 v12, v11
	v_mul_f32_e32 v11, 0xbfb8aa3b, v7
	v_exp_f32_e32 v11, v11
	v_add_f32_e32 v10, 1.0, v10
	v_exp_f32_e32 v15, v15
	v_rcp_f32_e32 v10, v10
	v_add_f32_e32 v11, 1.0, v11
	v_rcp_f32_e32 v11, v11
	v_add_f32_e32 v15, 1.0, v15
	v_mul_f32_e32 v13, 0xbfb8aa3b, v3
	v_mul_f32_e32 v14, 0xbfb8aa3b, v8
	v_rcp_f32_e32 v16, v15
	v_mul_f32_e32 v15, 0xbfb8aa3b, v9
	v_pk_mul_f32 v[6:7], v[6:7], v[10:11]
	v_mul_f32_e32 v10, 0xbfb8aa3b, v5
	v_exp_f32_e32 v13, v13
	v_exp_f32_e32 v14, v14
	v_exp_f32_e32 v15, v15
	v_exp_f32_e32 v10, v10
	v_add_f32_e32 v13, 1.0, v13
	v_add_f32_e32 v14, 1.0, v14
	v_add_f32_e32 v15, 1.0, v15
	v_add_f32_e32 v10, 1.0, v10
	v_rcp_f32_e32 v13, v13
	v_rcp_f32_e32 v14, v14
	v_rcp_f32_e32 v15, v15
	v_rcp_f32_e32 v17, v10
	v_pk_mul_f32 v[2:3], v[2:3], v[12:13]
	v_pk_mul_f32 v[8:9], v[8:9], v[14:15]
	v_pk_mul_f32 v[4:5], v[4:5], v[16:17]
	s_branch .LBB0_475

.LBB0_802:
	s_or_b64 exec, exec, s[28:29]
	s_cmp_lt_i32 s2, 0x100
	s_cselect_b64 s[0:1], -1, 0
	s_and_b64 s[0:1], s[0:1], s[48:49]
	s_andn2_b64 vcc, exec, s[0:1]
	s_cbranch_vccnz .LBB0_815
	v_ashrrev_i32_e32 v2, 7, v48
	v_ashrrev_i32_e32 v49, 31, v48
	v_lshlrev_b32_e64 v8, v2, 1
	v_lshl_add_u64 v[2:3], v[48:49], 1, s[26:27]
	s_mov_b64 s[0:1], 0x374c3400
	v_lshl_add_u64 v[2:3], v[2:3], 0, s[0:1]
	v_sub_u32_e32 v9, 0, v8
	v_sub_u32_e32 v10, 1, v8
	v_readlane_b32 s16, v255, 32
	s_mov_b32 s17, s2
	s_branch .LBB0_805
.LBB0_804:
	v_readlane_b32 s0, v255, 33
	s_add_i32 s17, s17, s62
	s_add_i32 s16, s16, s0
	s_cmp_gt_i32 s17, 0xff
	s_cbranch_scc1 .LBB0_815
.LBB0_805:
	s_lshl_b32 s16, s17, 3
	s_and_b32 s1, s16, 0xf8
	v_add_u32_e32 v11, s1, v10
	v_add_u32_e32 v12, s1, v9
	s_lshl_b32 s1, s17, 3
	s_and_b32 s18, s1, 0xf8
	s_and_b32 s1, s1, 0xffffff00
	s_and_b32 s0, s16, 0xffffff00
	s_mul_hi_i32 s10, s1, 0x2800
	s_mulk_i32 s1, 0x2800
	s_add_u32 s1, s24, s1
	s_addc_u32 s10, s25, s10
	s_add_u32 s19, s1, 0x28000000
	s_addc_u32 s28, s10, 0
	s_or_b32 s29, s18, 1
	v_mad_i64_i32 v[4:5], s[0:1], s0, v232, v[2:3]
	s_mov_b32 s30, 0
	s_branch .LBB0_807
.LBB0_806:
	s_or_b64 exec, exec, s[20:21]
	v_sub_u32_e32 v6, v14, v13
	v_cvt_f32_i32_e32 v6, v6
	s_mulk_i32 s10, 0x1400
	v_add_u32_e32 v12, 2, v12
	v_add_u32_e32 v11, 2, v11
	v_div_scale_f32 v7, s[0:1], v6, v6, v15
	v_rcp_f32_e32 v13, v7
	s_lshl_b64 s[0:1], s[10:11], 1
	s_add_u32 s0, s19, s0
	s_addc_u32 s1, s28, s1
	v_fma_f32 v14, -v7, v13, 1.0
	v_fmac_f32_e32 v13, v14, v13
	v_div_scale_f32 v14, vcc, v15, v6, v15
	v_mul_f32_e32 v16, v14, v13
	v_fma_f32 v17, -v7, v16, v14
	v_fmac_f32_e32 v16, v17, v13
	v_fma_f32 v7, -v7, v16, v14
	v_div_fmas_f32 v7, v7, v13, v16
	v_div_fixup_f32 v13, v7, v6, v15
	v_lshl_add_u64 v[6:7], v[48:49], 1, s[0:1]
	v_add_co_u32_e32 v14, vcc, 0x1000, v6
	s_add_i32 s30, s30, 2
	s_nop 0
	v_addc_co_u32_e32 v15, vcc, 0, v7, vcc
	global_load_ushort v14, v[14:15], off offset:1024
	s_cmp_eq_u32 s30, 8
	s_waitcnt vmcnt(0)
	v_lshlrev_b32_e32 v14, 16, v14
	v_sub_f32_e32 v13, v13, v14
	v_cvt_pk_bf16_f32 v13, v13, s0
	global_store_short v[6:7], v13, off
	s_cbranch_scc1 .LBB0_804
